# scan: VN = V Nak (all 4 v-tiles) computed by wave 5 alone (lightest wave/SIMD) instead of one tile each on waves 2,3,6,7
# speedup vs baseline: 1.0040x; 1.0040x over previous
; __device__ __forceinline__ uint2 pack4(f32x4 v) { uint2 u; u.x = cvt_pk_bf16(v[0], v[1]); u.y = cvt_pk_bf16(v[2], v[3]); return u; }
; #define MFMA16(a, b, c) __builtin_amdgcn_mfma_f32_16x16x32_bf16(a, b, c, 0, 0, 0)
; __device__ __forceinline__ void scan_phase(PREF p, char* smem, const int wid_u) {
;     ...
;       } else if (wave == 5) {
;         unsigned z0;
;         asm volatile("v_mov_b32 %0, 0" : "=v"(z0));
;         *(uint2*)(TT + (lane >> 2) * 40 + 16 + (lane & 3) * 4) = make_uint2(z0, z0);
;       } else if (wave == 2 || wave == 3 || wave >= 6) {
;         const int vtile = wave < 4 ? wave - 2 : wave - 4;
;         const bf16x8 vf = ldfrag(VT, 40, vtile * 16, 0, fr, fq);
;         const f32x4 zero = {0.f, 0.f, 0.f, 0.f};
; #pragma unroll
;         for (int tt = 0; tt < 2; ++tt) {
;           const f32x4 acc = MFMA16(ldfrag(NakT, 40, tt * 16, 0, fr, fq), vf, zero);
;           *(uint2*)(VNb + (vtile * 16 + fr) * 40 + tt * 16 + fq * 4) = pack4(acc);
;         }
;       }
.LBB0_552:
	s_cmp_eq_u32 s90, 5
	s_mov_b64 s[80:81], -1
	s_cbranch_scc0 .LBB0_554
	v_mov_b32 v56, 0
	s_mov_b64 s[80:81], 0
	v_mov_b32_e32 v57, v56
	ds_write_b64 v172, v[56:57] offset:13344
	v_add_u32_e32 v64, v130, v165
	ds_read_b128 v[56:59], v64 offset:4096
	ds_read_b128 v[66:69], v64 offset:5376
	v_add_u32_e32 v60, v131, v136
	v_add_u32_e32 v60, 0xfffffb00, v60
	ds_read_b128 v[94:97], v60
	ds_read_b128 v[98:101], v60 offset:1280
	ds_read_b128 v[102:105], v60 offset:2560
	ds_read_b128 v[106:109], v60 offset:3840
	s_waitcnt lgkmcnt(3)
	v_mfma_f32_16x16x32_bf16 v[190:193], v[56:59], v[94:97], 0
	v_mfma_f32_16x16x32_bf16 v[194:197], v[66:69], v[94:97], 0
	s_waitcnt lgkmcnt(2)
	v_mfma_f32_16x16x32_bf16 v[198:201], v[56:59], v[98:101], 0
	v_mfma_f32_16x16x32_bf16 v[202:205], v[66:69], v[98:101], 0
	s_waitcnt lgkmcnt(1)
	v_mfma_f32_16x16x32_bf16 v[206:209], v[56:59], v[102:105], 0
	v_mfma_f32_16x16x32_bf16 v[210:213], v[66:69], v[102:105], 0
	s_waitcnt lgkmcnt(0)
	v_mfma_f32_16x16x32_bf16 v[214:217], v[56:59], v[106:109], 0
	v_mfma_f32_16x16x32_bf16 v[218:221], v[66:69], v[106:109], 0
	v_cvt_pk_bf16_f32 v190, v190, v191
	v_cvt_pk_bf16_f32 v191, v192, v193
	ds_write_b64 v173, v[190:191] offset:38656
	v_cvt_pk_bf16_f32 v194, v194, v195
	v_cvt_pk_bf16_f32 v195, v196, v197
	ds_write_b64 v173, v[194:195] offset:38688
	v_cvt_pk_bf16_f32 v198, v198, v199
	v_cvt_pk_bf16_f32 v199, v200, v201
	ds_write_b64 v173, v[198:199] offset:39936
	v_cvt_pk_bf16_f32 v202, v202, v203
	v_cvt_pk_bf16_f32 v203, v204, v205
	ds_write_b64 v173, v[202:203] offset:39968
	v_cvt_pk_bf16_f32 v206, v206, v207
	v_cvt_pk_bf16_f32 v207, v208, v209
	ds_write_b64 v173, v[206:207] offset:41216
	v_cvt_pk_bf16_f32 v210, v210, v211
	v_cvt_pk_bf16_f32 v211, v212, v213
	ds_write_b64 v173, v[210:211] offset:41248
	s_nop 7
	v_cvt_pk_bf16_f32 v214, v214, v215
	v_cvt_pk_bf16_f32 v215, v216, v217
	ds_write_b64 v173, v[214:215] offset:42496
	v_cvt_pk_bf16_f32 v218, v218, v219
	v_cvt_pk_bf16_f32 v219, v220, v221
	ds_write_b64 v173, v[218:219] offset:42528

; __device__ __forceinline__ uint2 pack4(f32x4 v) { uint2 u; u.x = cvt_pk_bf16(v[0], v[1]); u.y = cvt_pk_bf16(v[2], v[3]); return u; }
; #define MFMA16(a, b, c) __builtin_amdgcn_mfma_f32_16x16x32_bf16(a, b, c, 0, 0, 0)
; __device__ __forceinline__ void scan_phase(PREF p, char* smem, const int wid_u) {
;     ...
;       } else if (wave == 2 || wave == 3 || wave >= 6) {
;         const int vtile = wave < 4 ? wave - 2 : wave - 4;
;         const bf16x8 vf = ldfrag(VT, 40, vtile * 16, 0, fr, fq);
;         const f32x4 zero = {0.f, 0.f, 0.f, 0.f};
; #pragma unroll
;         for (int tt = 0; tt < 2; ++tt) {
;           const f32x4 acc = MFMA16(ldfrag(NakT, 40, tt * 16, 0, fr, fq), vf, zero);
;           *(uint2*)(VNb + (vtile * 16 + fr) * 40 + tt * 16 + fq * 4) = pack4(acc);
;         }
;       }
.LBB0_556:
	s_andn2_b64 vcc, exec, s[66:67]
	s_cbranch_vccnz .LBB0_558
.LBB0_558:
	s_cbranch_execnz .LBB0_566
